# cache policy: the once-read f32 residual rows in prenorm0 and row-update A are loaded non-temporal (nt) so they do not displace reused data
# speedup vs baseline: 1.0093x; 1.0025x over previous
.LBB0_14:
	v_add_u32_e32 v9, 0xffffc000, v0
	v_cmp_gt_i32_e32 vcc, s69, v0
	v_mov_b32_e32 v11, s49
	v_mov_b32_e32 v24, s45
	v_cndmask_b32_e32 v23, 0, v1, vcc
	v_mov_b32_e32 v26, s48
	v_mov_b32_e32 v27, s44
	v_min_i32_e32 v28, 0x4000, v0
	v_cndmask_b32_e32 v22, v9, v0, vcc
	v_cndmask_b32_e32 v25, v11, v24, vcc
	v_cndmask_b32_e32 v24, v26, v27, vcc
	v_ashrrev_i32_e32 v9, 13, v28
	v_lshlrev_b64 v[22:23], 12, v[22:23]
	v_mul_hi_i32_i24_e32 v27, 0x6000, v9
	v_mul_i32_i24_e32 v26, 0x6000, v9
	v_lshl_add_u64 v[22:23], v[24:25], 0, v[22:23]
	v_lshl_add_u64 v[24:25], s[12:13], 0, v[26:27]
	v_lshl_add_u64 v[34:35], v[22:23], 0, v[192:193]
	global_load_dwordx4 v[18:21], v[2:3], off
	v_lshl_add_u64 v[46:47], v[24:25], 0, s[34:35]
	v_lshl_add_u64 v[48:49], v[24:25], 0, v[192:193]
	global_load_dwordx4 v[22:25], v[34:35], off nt
	global_load_dwordx4 v[26:29], v[34:35], off offset:1024 nt
	global_load_dwordx4 v[30:33], v[34:35], off offset:2048 nt
	s_nop 0
	global_load_dwordx4 v[34:37], v[34:35], off offset:3072 nt
	v_lshl_add_u64 v[38:39], v[46:47], 0, v[192:193]
	global_load_dwordx4 v[38:41], v[38:39], off
	s_nop 0
	global_load_dwordx4 v[42:45], v[48:49], off
	v_lshl_add_u64 v[96:97], v[46:47], 0, v[192:193]
	global_load_dwordx4 v[100:103], v[2:3], off offset:1024
	global_load_dwordx4 v[112:115], v[96:97], off offset:1024
	global_load_dwordx4 v[124:127], v[48:49], off offset:1024
	global_load_dwordx4 v[104:107], v[2:3], off offset:2048
	global_load_dwordx4 v[116:119], v[96:97], off offset:2048
	global_load_dwordx4 v[128:131], v[48:49], off offset:2048
	global_load_dwordx4 v[108:111], v[2:3], off offset:3072
	global_load_dwordx4 v[120:123], v[96:97], off offset:3072
	global_load_dwordx4 v[132:135], v[48:49], off offset:3072
	v_mov_b32_e32 v7, v193
	v_lshl_add_u64 v[50:51], v[46:47], 0, v[6:7]
	v_mov_b32_e32 v11, v193
	s_movk_i32 s2, 0x41ff
	v_lshl_add_u64 v[0:1], v[0:1], 0, s[38:39]
	v_cmp_lt_i32_e32 vcc, s2, v0
	s_or_b64 s[42:43], vcc, s[42:43]
	s_waitcnt vmcnt(14)
	v_mul_f32_e32 v7, v23, v23
	s_waitcnt vmcnt(13)
	v_mul_f32_e32 v9, v27, v27
	s_waitcnt vmcnt(12)
	v_mov_b32_e32 v54, v31
	s_waitcnt vmcnt(11)
	v_mov_b32_e32 v55, v35
	v_mov_b32_e32 v52, v30
	v_mov_b32_e32 v53, v34
	v_fmac_f32_e32 v7, v22, v22
	v_fmac_f32_e32 v9, v26, v26
	v_pk_mul_f32 v[54:55], v[54:55], v[54:55]
	v_mov_b32_e32 v56, v32
	v_mov_b32_e32 v57, v36
	v_fmac_f32_e32 v7, v24, v24
	v_fmac_f32_e32 v9, v28, v28
	v_pk_fma_f32 v[52:53], v[52:53], v[52:53], v[54:55]
	v_mov_b32_e32 v58, v33
	v_mov_b32_e32 v59, v37
	v_fmac_f32_e32 v7, v25, v25
	v_fmac_f32_e32 v9, v29, v29
	v_pk_fma_f32 v[52:53], v[56:57], v[56:57], v[52:53]
	v_add_f32_e32 v7, v7, v9
	v_pk_fma_f32 v[52:53], v[58:59], v[58:59], v[52:53]
	s_waitcnt vmcnt(10)
	v_pk_add_f32 v[38:39], v[38:39], 1.0 op_sel_hi:[1,0]
	v_add_f32_e32 v7, v7, v52
	v_add_f32_e32 v7, v7, v53
	v_pk_add_f32 v[40:41], v[40:41], 1.0 op_sel_hi:[1,0]
	s_waitcnt lgkmcnt(0)
	v_mov_b32_e32 v9, v7
	s_nop 1
	v_permlane32_swap_b32_e32 v9, v7
	v_add_f32_e32 v7, v7, v9
	v_mov_b32_e32 v9, v7
	s_nop 1
	v_permlane16_swap_b32_e32 v9, v7
	v_add_f32_e32 v7, v7, v9
	s_nop 1
	v_add_f32_dpp v7, v7, v7 row_ror:8 row_mask:0xf bank_mask:0xf
	s_nop 1
	v_add_f32_dpp v7, v7, v7 row_ror:4 row_mask:0xf bank_mask:0xf
	s_nop 1
	v_add_f32_dpp v7, v7, v7 row_ror:2 row_mask:0xf bank_mask:0xf
	s_nop 1
	v_add_f32_dpp v7, v7, v7 row_ror:1 row_mask:0xf bank_mask:0xf
	v_fmamk_f32 v7, v7, 0x3a800000, v221
	v_rsq_f32_e32 v52, v7
	v_mov_b32_e32 v9, v193
	v_pk_mul_f32 v[22:23], v[22:23], v[52:53] op_sel_hi:[1,0]
	v_pk_mul_f32 v[24:25], v[24:25], v[52:53] op_sel_hi:[1,0]
	v_pk_mul_f32 v[18:19], v[18:19], v[22:23]
	v_pk_mul_f32 v[20:21], v[20:21], v[24:25]
	s_waitcnt vmcnt(9)
	v_pk_fma_f32 v[18:19], v[38:39], v[18:19], v[42:43]
	v_pk_fma_f32 v[20:21], v[40:41], v[20:21], v[44:45]
	v_cvt_pk_bf16_f32 v18, v18, v19
	v_cvt_pk_bf16_f32 v19, v20, v21
	global_store_dwordx2 v[4:5], v[18:19], off
	s_nop 0
	s_nop 0
	s_nop 0
	s_nop 0
	v_pk_mul_f32 v[26:27], v[26:27], v[52:53] op_sel_hi:[1,0]
	v_pk_mul_f32 v[28:29], v[28:29], v[52:53] op_sel_hi:[1,0]
	v_lshl_add_u64 v[42:43], v[46:47], 0, v[8:9]
	v_pk_mul_f32 v[30:31], v[30:31], v[52:53] op_sel_hi:[1,0]
	v_pk_mul_f32 v[32:33], v[32:33], v[52:53] op_sel_hi:[1,0]
	s_waitcnt vmcnt(9)
	v_pk_mul_f32 v[18:19], v[100:101], v[26:27]
	s_waitcnt vmcnt(8)
	v_pk_add_f32 v[22:23], v[112:113], 1.0 op_sel_hi:[1,0]
	v_pk_mul_f32 v[20:21], v[102:103], v[28:29]
	v_pk_add_f32 v[24:25], v[114:115], 1.0 op_sel_hi:[1,0]
	s_waitcnt vmcnt(7)
	v_pk_fma_f32 v[18:19], v[22:23], v[18:19], v[124:125]
	v_pk_fma_f32 v[20:21], v[24:25], v[20:21], v[126:127]
	v_cvt_pk_bf16_f32 v18, v18, v19
	v_cvt_pk_bf16_f32 v19, v20, v21
	global_store_dwordx2 v[4:5], v[18:19], off offset:512
	s_nop 0
	s_nop 0
	s_nop 0
	s_nop 0
	v_lshl_add_u64 v[38:39], v[46:47], 0, v[10:11]
	s_waitcnt vmcnt(7)
	v_pk_mul_f32 v[18:19], v[30:31], v[104:105]
	s_waitcnt vmcnt(6)
	v_pk_add_f32 v[22:23], v[116:117], 1.0 op_sel_hi:[1,0]
	v_pk_mul_f32 v[20:21], v[32:33], v[106:107]
	v_pk_add_f32 v[24:25], v[118:119], 1.0 op_sel_hi:[1,0]
	s_waitcnt vmcnt(5)
	v_pk_fma_f32 v[18:19], v[18:19], v[22:23], v[128:129]
	v_pk_fma_f32 v[20:21], v[20:21], v[24:25], v[130:131]
	v_cvt_pk_bf16_f32 v18, v18, v19
	v_cvt_pk_bf16_f32 v19, v20, v21
	global_store_dwordx2 v[4:5], v[18:19], off offset:1024
	s_nop 0
	s_nop 0
	s_nop 0
	s_nop 0
	v_pk_mul_f32 v[30:31], v[34:35], v[52:53] op_sel_hi:[1,0]
	v_pk_mul_f32 v[32:33], v[36:37], v[52:53] op_sel_hi:[1,0]
	s_waitcnt vmcnt(5)
	v_pk_mul_f32 v[18:19], v[30:31], v[108:109]
	s_waitcnt vmcnt(4)
	v_pk_add_f32 v[22:23], v[120:121], 1.0 op_sel_hi:[1,0]
	v_pk_mul_f32 v[20:21], v[32:33], v[110:111]
	v_pk_add_f32 v[24:25], v[122:123], 1.0 op_sel_hi:[1,0]
	s_waitcnt vmcnt(3)
	v_pk_fma_f32 v[18:19], v[18:19], v[22:23], v[132:133]
	v_pk_fma_f32 v[20:21], v[20:21], v[24:25], v[134:135]
	v_cvt_pk_bf16_f32 v18, v18, v19
	v_cvt_pk_bf16_f32 v19, v20, v21
	global_store_dwordx2 v[4:5], v[18:19], off offset:1536
	v_lshl_add_u64 v[4:5], v[4:5], 0, s[40:41]
	s_andn2_b64 exec, exec, s[42:43]
	s_cbranch_execnz .LBB0_14

.LBB0_71:
	v_readlane_b32 s8, v253, 56
	v_readlane_b32 s12, v253, 60
	v_cmp_gt_i32_e64 s[0:1], s3, v24
	v_mov_b32_e32 v3, s8
	s_mov_b32 s8, s54
	v_readlane_b32 s48, v254, 9
	v_readlane_b32 s9, v253, 57
	v_readlane_b32 s10, v253, 58
	v_readlane_b32 s11, v253, 59
	v_readlane_b32 s13, v253, 61
	v_readlane_b32 s14, v253, 62
	v_readlane_b32 s15, v253, 63
	v_readlane_b32 s16, v254, 0
	v_readlane_b32 s17, v254, 1
	v_readlane_b32 s18, v254, 2
	v_readlane_b32 s19, v254, 3
	v_readlane_b32 s20, v254, 4
	v_readlane_b32 s21, v254, 5
	v_readlane_b32 s22, v254, 6
	v_readlane_b32 s23, v254, 7
	v_mov_b32_e32 v2, s12
	v_readlane_b32 s54, v254, 15
	v_cndmask_b32_e64 v2, v2, v3, s[0:1]
	v_mov_b32_e32 v3, s13
	v_mov_b32_e32 v4, s9
	s_mov_b32 s54, s8
	v_readlane_b32 s8, v254, 38
	v_readlane_b32 s61, v254, 22
	v_readlane_b32 s13, v254, 43
	v_cndmask_b32_e64 v3, v3, v4, s[0:1]
	v_readlane_b32 s60, v254, 21
	v_mov_b32_e32 v4, s61
	v_readlane_b32 s12, v254, 42
	v_mov_b32_e32 v5, s13
	v_add_u32_e32 v0, 0xffffc000, v24
	v_cndmask_b32_e64 v17, v4, v5, s[0:1]
	v_mov_b32_e32 v4, s60
	v_mov_b32_e32 v5, s12
	v_cndmask_b32_e64 v1, 0, v25, s[0:1]
	v_cndmask_b32_e64 v0, v0, v24, s[0:1]
	v_cndmask_b32_e64 v16, v4, v5, s[0:1]
	v_cndmask_b32_e32 v3, v17, v3, vcc
	v_cndmask_b32_e32 v2, v16, v2, vcc
	v_lshlrev_b64 v[18:19], 12, v[0:1]
	v_lshl_add_u64 v[0:1], v[2:3], 0, v[18:19]
	v_min_i32_e32 v2, 0x4000, v24
	v_readlane_b32 s52, v254, 13
	v_readlane_b32 s53, v254, 14
	v_ashrrev_i32_e32 v2, 13, v2
	s_mul_i32 s0, s54, 3
	v_add_u32_e32 v4, s0, v2
	v_mov_b64_e32 v[2:3], s[52:53]
	v_mad_i64_i32 v[42:43], s[0:1], v4, s67, v[2:3]
	v_lshl_add_u64 v[4:5], v[32:33], 0, v[30:31]
	v_lshl_add_u64 v[6:7], v[0:1], 0, v[192:193]
	global_load_dwordx2 v[54:55], v[4:5], off
	global_load_dwordx4 v[12:15], v[6:7], off nt
	global_load_dwordx2 v[58:59], v[4:5], off offset:512
	global_load_dwordx4 v[8:11], v[6:7], off offset:1024 nt
	global_load_dwordx2 v[20:21], v[4:5], off offset:1024
	global_load_dwordx4 v[0:3], v[6:7], off offset:2048 nt
	global_load_dwordx2 v[22:23], v[4:5], off offset:1536
	s_nop 0
	global_load_dwordx4 v[4:7], v[6:7], off offset:3072 nt
	v_lshl_add_u64 v[96:97], v[42:43], 0, v[192:193]
	s_mov_b64 s[0:1], 0x2000
	v_lshl_add_u64 v[98:99], v[96:97], 0, s[0:1]
	s_mov_b64 s[0:1], 0x3000
	v_lshl_add_u64 v[100:101], v[96:97], 0, s[0:1]
	s_mov_b64 s[0:1], 0x4000
	v_lshl_add_u64 v[102:103], v[96:97], 0, s[0:1]
	global_load_dwordx4 v[104:107], v[98:99], off
	global_load_dwordx4 v[120:123], v[26:27], off
	global_load_dwordx4 v[108:111], v[98:99], off offset:1024
	global_load_dwordx4 v[124:127], v[26:27], off offset:1024
	global_load_dwordx4 v[112:115], v[98:99], off offset:2048
	global_load_dwordx4 v[128:131], v[26:27], off offset:2048
	global_load_dwordx4 v[116:119], v[98:99], off offset:3072
	global_load_dwordx4 v[132:135], v[26:27], off offset:3072
	global_load_dwordx4 v[136:139], v[102:103], off
	global_load_dwordx4 v[152:155], v[100:101], off
	global_load_dwordx4 v[168:171], v[28:29], off
	global_load_dwordx4 v[172:175], v[28:29], off offset:1024
	global_load_dwordx4 v[140:143], v[102:103], off offset:1024
	global_load_dwordx4 v[156:159], v[100:101], off offset:1024
	global_load_dwordx4 v[176:179], v[28:29], off offset:2048
	global_load_dwordx4 v[144:147], v[102:103], off offset:2048
	global_load_dwordx4 v[160:163], v[100:101], off offset:2048
	global_load_dwordx4 v[180:183], v[28:29], off offset:3072
	global_load_dwordx4 v[148:151], v[102:103], off offset:3072
	global_load_dwordx4 v[164:167], v[100:101], off offset:3072
	s_mov_b64 s[0:1], 0x2000
	v_lshl_add_u64 v[52:53], v[42:43], 0, s[0:1]
	v_lshl_add_u64 v[72:73], v[16:17], 0, v[18:19]
	v_lshl_add_u64 v[16:17], v[52:53], 0, v[192:193]
	v_mov_b32_e32 v37, v193
	s_mov_b64 s[0:1], 0x4000
	v_lshl_add_u64 v[24:25], v[24:25], 0, s[40:41]
	v_lshl_add_u64 v[32:33], v[32:33], 0, s[42:43]
	v_readlane_b32 s49, v254, 10
	v_readlane_b32 s50, v254, 11
	v_readlane_b32 s51, v254, 12
	v_readlane_b32 s55, v254, 16
	v_readlane_b32 s56, v254, 17
	v_readlane_b32 s57, v254, 18
	v_readlane_b32 s58, v254, 19
	v_readlane_b32 s59, v254, 20
	v_readlane_b32 s62, v254, 23
	v_readlane_b32 s63, v254, 24
	v_readlane_b32 s9, v254, 39
	v_readlane_b32 s10, v254, 40
	v_readlane_b32 s11, v254, 41
	v_readlane_b32 s14, v254, 44
	v_readlane_b32 s15, v254, 45
	v_readlane_b32 s16, v254, 46
	v_readlane_b32 s17, v254, 47
	v_readlane_b32 s18, v254, 48
	v_readlane_b32 s19, v254, 49
	v_readlane_b32 s20, v254, 50
	v_readlane_b32 s21, v254, 51
	v_readlane_b32 s22, v254, 52
	v_readlane_b32 s23, v254, 53
	s_waitcnt vmcnt(27)
	v_lshlrev_b32_e32 v62, 16, v54
	v_and_b32_e32 v63, 0xffff0000, v54
	s_waitcnt vmcnt(25)
	v_lshlrev_b32_e32 v76, 16, v58
	v_and_b32_e32 v77, 0xffff0000, v58
	s_waitcnt vmcnt(23)
	v_and_b32_e32 v50, 0xffff0000, v20
	v_lshlrev_b32_e32 v48, 16, v20
	s_waitcnt vmcnt(21)
	v_and_b32_e32 v51, 0xffff0000, v22
	v_lshlrev_b32_e32 v49, 16, v22
	v_lshlrev_b32_e32 v44, 16, v21
	v_and_b32_e32 v46, 0xffff0000, v21
	v_pk_mul_f32 v[20:21], v[50:51], v[50:51]
	v_lshlrev_b32_e32 v45, 16, v23
	v_pk_fma_f32 v[20:21], v[48:49], v[48:49], v[20:21]
	v_and_b32_e32 v47, 0xffff0000, v23
	v_pk_fma_f32 v[20:21], v[44:45], v[44:45], v[20:21]
	v_pk_mul_f32 v[74:75], v[62:63], v[62:63]
	v_pk_fma_f32 v[56:57], v[46:47], v[46:47], v[20:21]
	s_nop 0
	s_nop 0
	s_nop 0
	v_lshlrev_b32_e32 v60, 16, v55
	v_and_b32_e32 v61, 0xffff0000, v55
	v_pk_mul_f32 v[78:79], v[76:77], v[76:77]
	v_lshlrev_b32_e32 v80, 16, v59
	v_and_b32_e32 v81, 0xffff0000, v59
	v_pk_mul_f32 v[64:65], v[60:61], v[60:61]
	v_pk_mul_f32 v[58:59], v[80:81], v[80:81]
	v_add_f32_e32 v39, v78, v79
	v_add_f32_e32 v41, v74, v75
	v_add_f32_e32 v39, v58, v39
	v_add_f32_e32 v41, v64, v41
	v_add_f32_e32 v39, v59, v39
	v_add_f32_e32 v41, v65, v41
	v_add_f32_e32 v39, v41, v39
	v_add_f32_e32 v39, v39, v56
	v_add_f32_e32 v39, v39, v57
	v_lshl_add_u64 v[54:55], v[72:73], 0, v[192:193]
	v_lshl_add_u64 v[72:73], v[52:53], 0, v[36:37]
	s_waitcnt lgkmcnt(0)
	v_mov_b32_e32 v41, v39
	s_nop 1
	v_permlane32_swap_b32_e32 v41, v39
	v_add_f32_e32 v39, v39, v41
	v_mov_b32_e32 v41, v39
	s_nop 1
	v_permlane16_swap_b32_e32 v41, v39
	v_add_f32_e32 v39, v39, v41
	s_nop 1
	v_add_f32_dpp v39, v39, v39 row_ror:8 row_mask:0xf bank_mask:0xf
	s_nop 1
	v_add_f32_dpp v39, v39, v39 row_ror:4 row_mask:0xf bank_mask:0xf
	s_nop 1
	v_add_f32_dpp v39, v39, v39 row_ror:2 row_mask:0xf bank_mask:0xf
	s_nop 1
	v_add_f32_dpp v39, v39, v39 row_ror:1 row_mask:0xf bank_mask:0xf
	v_fmamk_f32 v39, v39, 0x3a800000, v221
	v_rsq_f32_e32 v56, v39
	v_mov_b32_e32 v39, v193
	v_mov_b32_e32 v41, v193
	v_pk_mul_f32 v[58:59], v[56:57], v[62:63] op_sel_hi:[0,1]
	v_pk_mul_f32 v[62:63], v[56:57], v[76:77] op_sel_hi:[0,1]
	s_waitcnt vmcnt(18)
	v_pk_mul_f32 v[20:21], v[120:121], v[58:59]
	s_nop 0
	v_pk_fma_f32 v[12:13], v[104:105], v[20:21], v[12:13]
	v_pk_mul_f32 v[20:21], v[56:57], v[60:61] op_sel_hi:[0,1]
	v_pk_mul_f32 v[20:21], v[122:123], v[20:21]
	v_pk_mul_f32 v[16:17], v[12:13], v[12:13]
	v_pk_fma_f32 v[14:15], v[106:107], v[20:21], v[14:15]
	global_store_dwordx4 v[54:55], v[12:15], off
	s_nop 0
	s_nop 0
	v_mov_b32_e32 v72, v48
	v_mov_b32_e32 v73, v50
	v_pk_mul_f32 v[72:73], v[56:57], v[72:73] op_sel_hi:[0,1]
	v_pk_mul_f32 v[18:19], v[14:15], v[14:15]
	v_add_f32_e32 v16, v16, v17
	v_add_f32_e32 v16, v18, v16
	v_add_f32_e32 v16, v19, v16
	v_mov_b32_e32 v50, v49
	v_pk_mul_f32 v[48:49], v[56:57], v[50:51] op_sel_hi:[0,1]
	s_waitcnt vmcnt(17)
	v_pk_mul_f32 v[58:59], v[124:125], v[62:63]
	s_nop 0
	v_pk_fma_f32 v[8:9], v[108:109], v[58:59], v[8:9]
	v_pk_mul_f32 v[20:21], v[56:57], v[80:81] op_sel_hi:[0,1]
	v_pk_mul_f32 v[20:21], v[126:127], v[20:21]
	v_pk_mul_f32 v[62:63], v[8:9], v[8:9]
	v_pk_fma_f32 v[10:11], v[110:111], v[20:21], v[10:11]
	global_store_dwordx4 v[54:55], v[8:11], off offset:1024
	v_lshl_add_u64 v[20:21], v[52:53], 0, v[38:39]
	s_nop 0
	s_nop 0
	s_nop 0
	v_add_f32_e32 v16, v62, v16
	v_pk_mul_f32 v[64:65], v[10:11], v[10:11]
	v_add_f32_e32 v16, v63, v16
	v_add_f32_e32 v16, v64, v16
	v_add_f32_e32 v16, v65, v16
	s_waitcnt vmcnt(16)
	v_pk_mul_f32 v[58:59], v[128:129], v[72:73]
	s_nop 0
	v_pk_fma_f32 v[0:1], v[112:113], v[58:59], v[0:1]
	v_mov_b32_e32 v20, v44
	v_mov_b32_e32 v21, v46
	v_pk_mul_f32 v[20:21], v[56:57], v[20:21] op_sel_hi:[0,1]
	v_pk_mul_f32 v[20:21], v[130:131], v[20:21]
	v_pk_mul_f32 v[72:73], v[0:1], v[0:1]
	v_pk_fma_f32 v[2:3], v[114:115], v[20:21], v[2:3]
	global_store_dwordx4 v[54:55], v[0:3], off offset:2048
	v_lshl_add_u64 v[20:21], v[52:53], 0, v[40:41]
	s_nop 0
	s_nop 0
	s_nop 0
	v_add_f32_e32 v16, v72, v16
	v_pk_mul_f32 v[74:75], v[2:3], v[2:3]
	v_mov_b32_e32 v46, v45
	v_add_f32_e32 v16, v73, v16
	v_pk_mul_f32 v[44:45], v[56:57], v[46:47] op_sel_hi:[0,1]
	v_add_f32_e32 v16, v74, v16
	v_add_f32_e32 v16, v75, v16
	s_waitcnt vmcnt(15)
	v_pk_mul_f32 v[48:49], v[48:49], v[132:133]
	s_nop 0
	v_pk_fma_f32 v[4:5], v[116:117], v[48:49], v[4:5]
	v_pk_mul_f32 v[44:45], v[44:45], v[134:135]
	v_pk_mul_f32 v[20:21], v[4:5], v[4:5]
	v_pk_fma_f32 v[6:7], v[118:119], v[44:45], v[6:7]
	v_add_f32_e32 v16, v20, v16
	v_pk_mul_f32 v[22:23], v[6:7], v[6:7]
	v_add_f32_e32 v16, v21, v16
	v_add_f32_e32 v16, v22, v16
	v_add_f32_e32 v16, v23, v16
	v_lshl_add_u64 v[44:45], v[42:43], 0, s[0:1]
	s_mov_b64 s[0:1], 0x3000
	global_store_dwordx4 v[54:55], v[4:7], off offset:3072
	v_lshl_add_u64 v[22:23], v[42:43], 0, s[0:1]
	s_waitcnt lgkmcnt(0)
	v_mov_b32_e32 v17, v16
	s_nop 1
	v_permlane32_swap_b32_e32 v17, v16
	v_add_f32_e32 v16, v16, v17
	v_lshl_add_u64 v[42:43], v[44:45], 0, v[192:193]
	s_nop 0
	v_lshl_add_u64 v[42:43], v[22:23], 0, v[192:193]
	s_nop 0
	v_mov_b32_e32 v17, v16
	s_nop 1
	v_permlane16_swap_b32_e32 v17, v16
	v_add_f32_e32 v16, v16, v17
	v_lshl_add_u64 v[42:43], v[34:35], 0, v[30:31]
	v_cmp_le_i32_e64 s[0:1], s2, v24
	v_lshl_add_u64 v[34:35], v[34:35], 0, s[42:43]
	s_or_b64 s[44:45], s[0:1], s[44:45]
	s_nop 1
	v_add_f32_dpp v16, v16, v16 row_ror:8 row_mask:0xf bank_mask:0xf
	s_nop 1
	v_add_f32_dpp v16, v16, v16 row_ror:4 row_mask:0xf bank_mask:0xf
	s_nop 1
	v_add_f32_dpp v16, v16, v16 row_ror:2 row_mask:0xf bank_mask:0xf
	s_nop 1
	v_add_f32_dpp v16, v16, v16 row_ror:1 row_mask:0xf bank_mask:0xf
	v_fmamk_f32 v16, v16, 0x3a800000, v221
	v_rsq_f32_e32 v20, v16
	s_nop 0
	v_pk_mul_f32 v[12:13], v[12:13], v[20:21] op_sel_hi:[1,0]
	v_pk_mul_f32 v[14:15], v[14:15], v[20:21] op_sel_hi:[1,0]
	v_pk_mul_f32 v[8:9], v[8:9], v[20:21] op_sel_hi:[1,0]
	v_pk_mul_f32 v[10:11], v[10:11], v[20:21] op_sel_hi:[1,0]
	v_pk_mul_f32 v[0:1], v[0:1], v[20:21] op_sel_hi:[1,0]
	v_pk_mul_f32 v[2:3], v[2:3], v[20:21] op_sel_hi:[1,0]
	v_pk_mul_f32 v[4:5], v[4:5], v[20:21] op_sel_hi:[1,0]
	s_waitcnt vmcnt(13)
	v_pk_mul_f32 v[12:13], v[168:169], v[12:13]
	v_pk_add_f32 v[16:17], v[136:137], 1.0 op_sel_hi:[1,0]
	v_pk_mul_f32 v[14:15], v[170:171], v[14:15]
	v_pk_fma_f32 v[12:13], v[16:17], v[12:13], v[152:153]
	v_pk_add_f32 v[16:17], v[138:139], 1.0 op_sel_hi:[1,0]
	v_cvt_pk_bf16_f32 v12, v12, v13
	v_pk_fma_f32 v[14:15], v[16:17], v[14:15], v[154:155]
	v_lshl_add_u64 v[16:17], v[44:45], 0, v[36:37]
	v_cvt_pk_bf16_f32 v13, v14, v15
	global_store_dwordx2 v[42:43], v[12:13], off
	s_nop 0
	v_lshl_add_u64 v[46:47], v[22:23], 0, v[36:37]
	s_nop 0
	s_waitcnt vmcnt(13)
	v_pk_mul_f32 v[8:9], v[172:173], v[8:9]
	s_nop 0
	s_waitcnt vmcnt(12)
	v_pk_add_f32 v[12:13], v[140:141], 1.0 op_sel_hi:[1,0]
	v_pk_mul_f32 v[10:11], v[174:175], v[10:11]
	v_lshl_add_u64 v[16:17], v[22:23], 0, v[38:39]
	s_waitcnt vmcnt(11)
	v_pk_fma_f32 v[8:9], v[12:13], v[8:9], v[156:157]
	v_pk_add_f32 v[12:13], v[142:143], 1.0 op_sel_hi:[1,0]
	v_cvt_pk_bf16_f32 v8, v8, v9
	v_pk_fma_f32 v[10:11], v[12:13], v[10:11], v[158:159]
	v_lshl_add_u64 v[12:13], v[44:45], 0, v[38:39]
	v_cvt_pk_bf16_f32 v9, v10, v11
	global_store_dwordx2 v[42:43], v[8:9], off offset:512
	s_nop 0
	s_waitcnt vmcnt(11)
	v_pk_mul_f32 v[0:1], v[176:177], v[0:1]
	s_nop 0
	v_pk_mul_f32 v[2:3], v[178:179], v[2:3]
	s_nop 0
	s_waitcnt vmcnt(10)
	v_pk_add_f32 v[8:9], v[144:145], 1.0 op_sel_hi:[1,0]
	v_lshl_add_u64 v[12:13], v[22:23], 0, v[40:41]
	s_waitcnt vmcnt(9)
	v_pk_fma_f32 v[0:1], v[8:9], v[0:1], v[160:161]
	v_pk_add_f32 v[8:9], v[146:147], 1.0 op_sel_hi:[1,0]
	v_cvt_pk_bf16_f32 v0, v0, v1
	v_pk_fma_f32 v[2:3], v[8:9], v[2:3], v[162:163]
	v_lshl_add_u64 v[8:9], v[44:45], 0, v[40:41]
	v_cvt_pk_bf16_f32 v1, v2, v3
	global_store_dwordx2 v[42:43], v[0:1], off offset:1024
	s_nop 0
	s_waitcnt vmcnt(9)
	v_pk_mul_f32 v[0:1], v[180:181], v[4:5]
	s_nop 0
	s_waitcnt vmcnt(8)
	v_pk_add_f32 v[4:5], v[148:149], 1.0 op_sel_hi:[1,0]
	s_nop 0
	s_waitcnt vmcnt(7)
	v_pk_fma_f32 v[0:1], v[4:5], v[0:1], v[164:165]
	v_pk_mul_f32 v[4:5], v[6:7], v[20:21] op_sel_hi:[1,0]
	v_cvt_pk_bf16_f32 v0, v0, v1
	v_pk_mul_f32 v[2:3], v[182:183], v[4:5]
	v_pk_add_f32 v[4:5], v[150:151], 1.0 op_sel_hi:[1,0]
	s_nop 0
	v_pk_fma_f32 v[2:3], v[4:5], v[2:3], v[166:167]
	s_nop 0
	v_cvt_pk_bf16_f32 v1, v2, v3
	global_store_dwordx2 v[42:43], v[0:1], off offset:1536
	s_andn2_b64 exec, exec, s[44:45]
	s_cbranch_execnz .LBB0_71
